# phases 1a (pre rmsnorm) and 9 (rowmid) rewritten by hand like phase 12: loads issued up front, next-row prefetch, per-batch constants hoisted
# speedup vs baseline: 1.0069x; 1.0069x over previous
; DI unsigned pk2(float lo, float hi) { f32x2 v = {lo, hi}; bfv2 r = __builtin_convertvector(v, bfv2); return __builtin_bit_cast(unsigned, r); }
; DI float wave_sum(float v) { for (int m = 32; m >= 1; m >>= 1) v += __shfl_xor(v, m, 64); return v; }
; DI void phase_pre(const P& p, int bid, int nb) {
;     ...
;   for (int row = bid * 8 + wid; row < TC; row += nb * 8) {
;     const float* src; int mrow;
;     if (row < T) { src = p.x + (size_t)row * D; mrow = row >> 14; } else { src = p.ctx + (size_t)(row - T) * D; mrow = 2; }
;     f32x4 v[8]; float ss = 0.f;
; #pragma unroll
;     for (int q = 0; q < 8; ++q) { v[q] = *(const f32x4*)(src + q * 256 + lane * 4); ss += v[q].x * v[q].x + v[q].y * v[q].y + v[q].z * v[q].z + v[q].w * v[q].w; }
;     ss = wave_sum(ss); const float rstd = rsqrtf(ss * (1.f / 2048.f) + 1e-6f);
;     const float* sh = MOD + mrow * 12288; const float* sc = sh + 2048;
; #pragma unroll
;     for (int q = 0; q < 8; ++q) { int idx = q * 256 + lane * 4; f32x4 w = *(const f32x4*)(p.n_pre_mix + idx), s1 = *(const f32x4*)(sc + idx), h1 = *(const f32x4*)(sh + idx);
;       f32x4 y = v[q] * rstd * w * (1.f + s1) + h1; u32x2 o; o.x = pk2(y.x, y.y); o.y = pk2(y.z, y.w); *(u32x2*)(HX + (size_t)row * D + idx) = o; }
.LBB0_57:
	v_lshrrev_b32_e32 v28, 6, v2
	s_lshl_b32 s8, s2, 3
	v_and_b32_e32 v3, 63, v2
	v_add_u32_e32 v1, s8, v28
	v_lshlrev_b32_e32 v30, 2, v3
	s_mov_b64 s[4:5], exec
	v_lshlrev_b32_e32 v4, 4, v3
	v_readfirstlane_b32 s3, v1
	v_lshlrev_b32_e32 v5, 5, v3
	v_xor_b32_e32 v6, 32, v3
	v_lshlrev_b32_e32 v6, 2, v6
	v_xor_b32_e32 v7, 16, v3
	v_lshlrev_b32_e32 v7, 2, v7
	v_xor_b32_e32 v8, 8, v3
	v_lshlrev_b32_e32 v8, 2, v8
	v_xor_b32_e32 v9, 4, v3
	v_lshlrev_b32_e32 v9, 2, v9
	v_xor_b32_e32 v10, 2, v3
	v_lshlrev_b32_e32 v10, 2, v10
	v_xor_b32_e32 v11, 1, v3
	v_lshlrev_b32_e32 v11, 2, v11
	s_lshl_b32 s6, s88, 3
	s_mov_b32 s22, 0x8000
	s_mov_b32 s23, 0x8200
	s_cmp_ge_i32 s3, s23
	s_cbranch_scc1 .LBB0_64
	s_mov_b32 s7, -1
	s_add_u32 s20, s80, 0x1000
	s_addc_u32 s21, s81, 0
	global_load_dwordx4 v[32:35], v5, s[80:81]
	global_load_dwordx4 v[36:39], v5, s[80:81] offset:16
	global_load_dwordx4 v[40:43], v5, s[80:81] offset:2048
	global_load_dwordx4 v[44:47], v5, s[80:81] offset:2064
	global_load_dwordx4 v[48:51], v5, s[20:21]
	global_load_dwordx4 v[52:55], v5, s[20:21] offset:16
	global_load_dwordx4 v[56:59], v5, s[20:21] offset:2048
	global_load_dwordx4 v[60:63], v5, s[20:21] offset:2064
	s_cmp_lt_i32 s3, s22
	s_cselect_b32 s24, s68, s72
	s_cselect_b32 s25, s69, s73
	s_cselect_b32 s18, 0, s22
	s_sub_i32 s18, s3, s18
	s_lshl_b32 s18, s18, 13
	s_add_u32 s8, s24, s18
	s_addc_u32 s9, s25, 0
	s_add_u32 s10, s8, 0x1000
	s_addc_u32 s11, s9, 0
	global_load_dwordx4 v[128:131], v5, s[8:9]
	global_load_dwordx4 v[132:135], v5, s[8:9] offset:16
	global_load_dwordx4 v[136:139], v5, s[8:9] offset:2048
	global_load_dwordx4 v[140:143], v5, s[8:9] offset:2064
	global_load_dwordx4 v[144:147], v5, s[10:11]
	global_load_dwordx4 v[148:151], v5, s[10:11] offset:16
	global_load_dwordx4 v[152:155], v5, s[10:11] offset:2048
	global_load_dwordx4 v[156:159], v5, s[10:11] offset:2064
.Lpre_half_A:
	s_lshr_b32 s18, s3, 14
	s_min_u32 s18, s18, 2
	s_cmp_eq_u32 s18, s7
	s_cbranch_scc1 .Lpre_mok_A
	s_mov_b32 s7, s18
	s_mul_i32 s18, s18, 0xc000
	s_add_u32 s14, s84, s18
	s_addc_u32 s15, s85, 0
	global_load_dwordx4 v[96:99], v5, s[14:15]
	global_load_dwordx4 v[100:103], v5, s[14:15] offset:16
	global_load_dwordx4 v[104:107], v5, s[14:15] offset:2048
	global_load_dwordx4 v[108:111], v5, s[14:15] offset:2064
	s_add_u32 s14, s14, 0x1000
	s_addc_u32 s15, s15, 0
	global_load_dwordx4 v[112:115], v5, s[14:15]
	global_load_dwordx4 v[116:119], v5, s[14:15] offset:16
	global_load_dwordx4 v[120:123], v5, s[14:15] offset:2048
	global_load_dwordx4 v[124:127], v5, s[14:15] offset:2064
	s_add_u32 s14, s14, 0x1000
	s_addc_u32 s15, s15, 0
	global_load_dwordx4 v[64:67], v5, s[14:15]
	global_load_dwordx4 v[68:71], v5, s[14:15] offset:16
	global_load_dwordx4 v[72:75], v5, s[14:15] offset:2048
	global_load_dwordx4 v[76:79], v5, s[14:15] offset:2064
	s_add_u32 s14, s14, 0x1000
	s_addc_u32 s15, s15, 0
	global_load_dwordx4 v[80:83], v5, s[14:15]
	global_load_dwordx4 v[84:87], v5, s[14:15] offset:16
	global_load_dwordx4 v[88:91], v5, s[14:15] offset:2048
	global_load_dwordx4 v[92:95], v5, s[14:15] offset:2064
	s_add_u32 s14, s14, 0x1000
	s_addc_u32 s15, s15, 0
	s_waitcnt vmcnt(0)
	v_pk_add_f32 v[64:65], v[64:65], 1.0 op_sel_hi:[1,0]
	v_pk_add_f32 v[66:67], v[66:67], 1.0 op_sel_hi:[1,0]
	v_pk_add_f32 v[68:69], v[68:69], 1.0 op_sel_hi:[1,0]
	v_pk_add_f32 v[70:71], v[70:71], 1.0 op_sel_hi:[1,0]
	v_pk_add_f32 v[72:73], v[72:73], 1.0 op_sel_hi:[1,0]
	v_pk_add_f32 v[74:75], v[74:75], 1.0 op_sel_hi:[1,0]
	v_pk_add_f32 v[76:77], v[76:77], 1.0 op_sel_hi:[1,0]
	v_pk_add_f32 v[78:79], v[78:79], 1.0 op_sel_hi:[1,0]
	v_pk_add_f32 v[80:81], v[80:81], 1.0 op_sel_hi:[1,0]
	v_pk_add_f32 v[82:83], v[82:83], 1.0 op_sel_hi:[1,0]
	v_pk_add_f32 v[84:85], v[84:85], 1.0 op_sel_hi:[1,0]
	v_pk_add_f32 v[86:87], v[86:87], 1.0 op_sel_hi:[1,0]
	v_pk_add_f32 v[88:89], v[88:89], 1.0 op_sel_hi:[1,0]
	v_pk_add_f32 v[90:91], v[90:91], 1.0 op_sel_hi:[1,0]
	v_pk_add_f32 v[92:93], v[92:93], 1.0 op_sel_hi:[1,0]
	v_pk_add_f32 v[94:95], v[94:95], 1.0 op_sel_hi:[1,0]
; DI unsigned pk2(float lo, float hi) { f32x2 v = {lo, hi}; bfv2 r = __builtin_convertvector(v, bfv2); return __builtin_bit_cast(unsigned, r); }
; DI float wave_sum(float v) { for (int m = 32; m >= 1; m >>= 1) v += __shfl_xor(v, m, 64); return v; }
; DI void phase_pre(const P& p, int bid, int nb) {
;     ...
;     f32x4 v[8]; float ss = 0.f;
; #pragma unroll
;     for (int q = 0; q < 8; ++q) { v[q] = *(const f32x4*)(src + q * 256 + lane * 4); ss += v[q].x * v[q].x + v[q].y * v[q].y + v[q].z * v[q].z + v[q].w * v[q].w; }
;     ss = wave_sum(ss); const float rstd = rsqrtf(ss * (1.f / 2048.f) + 1e-6f);
;     const float* sh = MOD + mrow * 12288; const float* sc = sh + 2048;
; #pragma unroll
;     for (int q = 0; q < 8; ++q) { int idx = q * 256 + lane * 4; f32x4 w = *(const f32x4*)(p.n_pre_mix + idx), s1 = *(const f32x4*)(sc + idx), h1 = *(const f32x4*)(sh + idx);
;       f32x4 y = v[q] * rstd * w * (1.f + s1) + h1; u32x2 o; o.x = pk2(y.x, y.y); o.y = pk2(y.z, y.w); *(u32x2*)(HX + (size_t)row * D + idx) = o; }
.Lpre_mok_A:
	s_add_i32 s17, s3, s6
	s_cmp_lt_i32 s17, s23
	s_cselect_b32 s16, 1, 0
	s_cselect_b32 s19, s17, s3
	s_cmp_lt_i32 s19, s22
	s_cselect_b32 s24, s68, s72
	s_cselect_b32 s25, s69, s73
	s_cselect_b32 s18, 0, s22
	s_sub_i32 s18, s19, s18
	s_lshl_b32 s18, s18, 13
	s_add_u32 s8, s24, s18
	s_addc_u32 s9, s25, 0
	s_add_u32 s10, s8, 0x1000
	s_addc_u32 s11, s9, 0
	s_lshl_b32 s18, s3, 12
	s_add_u32 s12, s84, s18
	s_addc_u32 s13, s85, 0
	s_add_u32 s12, s12, 0x1000000
	s_addc_u32 s13, s13, 0
	global_load_dwordx4 v[160:163], v5, s[8:9]
	global_load_dwordx4 v[164:167], v5, s[8:9] offset:16
	global_load_dwordx4 v[168:171], v5, s[8:9] offset:2048
	global_load_dwordx4 v[172:175], v5, s[8:9] offset:2064
	global_load_dwordx4 v[176:179], v5, s[10:11]
	global_load_dwordx4 v[180:183], v5, s[10:11] offset:16
	global_load_dwordx4 v[184:187], v5, s[10:11] offset:2048
	global_load_dwordx4 v[188:191], v5, s[10:11] offset:2064
	s_waitcnt vmcnt(12)
	v_mul_f32_e32 v208, v128, v128
	v_fmac_f32_e32 v208, v132, v132
	v_mul_f32_e32 v209, v136, v136
	v_fmac_f32_e32 v209, v140, v140
	v_mul_f32_e32 v210, v144, v144
	v_fmac_f32_e32 v210, v148, v148
	v_mul_f32_e32 v211, v152, v152
	v_fmac_f32_e32 v211, v156, v156
	v_fmac_f32_e32 v208, v129, v129
	v_fmac_f32_e32 v208, v133, v133
	v_fmac_f32_e32 v209, v137, v137
	v_fmac_f32_e32 v209, v141, v141
	v_fmac_f32_e32 v210, v145, v145
	v_fmac_f32_e32 v210, v149, v149
	v_fmac_f32_e32 v211, v153, v153
	v_fmac_f32_e32 v211, v157, v157
	v_fmac_f32_e32 v208, v130, v130
	v_fmac_f32_e32 v208, v134, v134
	v_fmac_f32_e32 v209, v138, v138
	v_fmac_f32_e32 v209, v142, v142
	v_fmac_f32_e32 v210, v146, v146
	v_fmac_f32_e32 v210, v150, v150
	v_fmac_f32_e32 v211, v154, v154
	v_fmac_f32_e32 v211, v158, v158
	v_fmac_f32_e32 v208, v131, v131
	v_fmac_f32_e32 v208, v135, v135
	v_fmac_f32_e32 v209, v139, v139
	v_fmac_f32_e32 v209, v143, v143
	v_fmac_f32_e32 v210, v147, v147
	v_fmac_f32_e32 v210, v151, v151
	v_fmac_f32_e32 v211, v155, v155
	v_fmac_f32_e32 v211, v159, v159
	v_add_f32_e32 v208, v208, v209
	v_add_f32_e32 v210, v210, v211
	v_add_f32_e32 v208, v208, v210
	ds_bpermute_b32 v212, v6, v208
	s_waitcnt lgkmcnt(0)
	v_add_f32_e32 v208, v208, v212
	ds_bpermute_b32 v212, v7, v208
	s_waitcnt lgkmcnt(0)
	v_add_f32_e32 v208, v208, v212
	ds_bpermute_b32 v212, v8, v208
	s_waitcnt lgkmcnt(0)
	v_add_f32_e32 v208, v208, v212
	ds_bpermute_b32 v212, v9, v208
	s_waitcnt lgkmcnt(0)
	v_add_f32_e32 v208, v208, v212
	ds_bpermute_b32 v212, v10, v208
	s_waitcnt lgkmcnt(0)
	v_add_f32_e32 v208, v208, v212
	ds_bpermute_b32 v212, v11, v208
	s_waitcnt lgkmcnt(0)
	v_add_f32_e32 v208, v208, v212
	v_mov_b32_e32 v212, 0x358637bd
	v_fmac_f32_e32 v212, 0x3a000000, v208
	v_rsq_f32_e32 v214, v212
	s_nop 0
	v_pk_mul_f32 v[128:129], v[214:215], v[128:129] op_sel_hi:[0,1]
	v_pk_mul_f32 v[130:131], v[214:215], v[130:131] op_sel_hi:[0,1]
	v_pk_mul_f32 v[128:129], v[128:129], v[32:33]
	v_pk_mul_f32 v[130:131], v[130:131], v[34:35]
	v_pk_fma_f32 v[128:129], v[128:129], v[64:65], v[96:97]
	v_pk_fma_f32 v[130:131], v[130:131], v[66:67], v[98:99]
	v_cvt_pk_bf16_f32 v192, v128, v129
	v_cvt_pk_bf16_f32 v193, v130, v131
	v_pk_mul_f32 v[132:133], v[214:215], v[132:133] op_sel_hi:[0,1]
	v_pk_mul_f32 v[134:135], v[214:215], v[134:135] op_sel_hi:[0,1]
	v_pk_mul_f32 v[132:133], v[132:133], v[36:37]
	v_pk_mul_f32 v[134:135], v[134:135], v[38:39]
	v_pk_fma_f32 v[132:133], v[132:133], v[68:69], v[100:101]
	v_pk_fma_f32 v[134:135], v[134:135], v[70:71], v[102:103]
	v_cvt_pk_bf16_f32 v194, v132, v133
	v_cvt_pk_bf16_f32 v195, v134, v135
	global_store_dwordx4 v4, v[192:195], s[12:13]
	v_pk_mul_f32 v[136:137], v[214:215], v[136:137] op_sel_hi:[0,1]
	v_pk_mul_f32 v[138:139], v[214:215], v[138:139] op_sel_hi:[0,1]
	v_pk_mul_f32 v[136:137], v[136:137], v[40:41]
	v_pk_mul_f32 v[138:139], v[138:139], v[42:43]
	v_pk_fma_f32 v[136:137], v[136:137], v[72:73], v[104:105]
	v_pk_fma_f32 v[138:139], v[138:139], v[74:75], v[106:107]
	v_cvt_pk_bf16_f32 v196, v136, v137
	v_cvt_pk_bf16_f32 v197, v138, v139
	v_pk_mul_f32 v[140:141], v[214:215], v[140:141] op_sel_hi:[0,1]
	v_pk_mul_f32 v[142:143], v[214:215], v[142:143] op_sel_hi:[0,1]
	v_pk_mul_f32 v[140:141], v[140:141], v[44:45]
	v_pk_mul_f32 v[142:143], v[142:143], v[46:47]
	v_pk_fma_f32 v[140:141], v[140:141], v[76:77], v[108:109]
	v_pk_fma_f32 v[142:143], v[142:143], v[78:79], v[110:111]
	v_cvt_pk_bf16_f32 v198, v140, v141
	v_cvt_pk_bf16_f32 v199, v142, v143
	global_store_dwordx4 v4, v[196:199], s[12:13] offset:1024
	v_pk_mul_f32 v[144:145], v[214:215], v[144:145] op_sel_hi:[0,1]
	v_pk_mul_f32 v[146:147], v[214:215], v[146:147] op_sel_hi:[0,1]
	v_pk_mul_f32 v[144:145], v[144:145], v[48:49]
	v_pk_mul_f32 v[146:147], v[146:147], v[50:51]
	v_pk_fma_f32 v[144:145], v[144:145], v[80:81], v[112:113]
	v_pk_fma_f32 v[146:147], v[146:147], v[82:83], v[114:115]
	v_cvt_pk_bf16_f32 v200, v144, v145
	v_cvt_pk_bf16_f32 v201, v146, v147
	v_pk_mul_f32 v[148:149], v[214:215], v[148:149] op_sel_hi:[0,1]
	v_pk_mul_f32 v[150:151], v[214:215], v[150:151] op_sel_hi:[0,1]
	v_pk_mul_f32 v[148:149], v[148:149], v[52:53]
	v_pk_mul_f32 v[150:151], v[150:151], v[54:55]
	v_pk_fma_f32 v[148:149], v[148:149], v[84:85], v[116:117]
	v_pk_fma_f32 v[150:151], v[150:151], v[86:87], v[118:119]
	v_cvt_pk_bf16_f32 v202, v148, v149
	v_cvt_pk_bf16_f32 v203, v150, v151
	global_store_dwordx4 v4, v[200:203], s[12:13] offset:2048
	v_pk_mul_f32 v[152:153], v[214:215], v[152:153] op_sel_hi:[0,1]
	v_pk_mul_f32 v[154:155], v[214:215], v[154:155] op_sel_hi:[0,1]
	v_pk_mul_f32 v[152:153], v[152:153], v[56:57]
	v_pk_mul_f32 v[154:155], v[154:155], v[58:59]
	v_pk_fma_f32 v[152:153], v[152:153], v[88:89], v[120:121]
	v_pk_fma_f32 v[154:155], v[154:155], v[90:91], v[122:123]
	v_cvt_pk_bf16_f32 v204, v152, v153
	v_cvt_pk_bf16_f32 v205, v154, v155
	v_pk_mul_f32 v[156:157], v[214:215], v[156:157] op_sel_hi:[0,1]
	v_pk_mul_f32 v[158:159], v[214:215], v[158:159] op_sel_hi:[0,1]
	v_pk_mul_f32 v[156:157], v[156:157], v[60:61]
	v_pk_mul_f32 v[158:159], v[158:159], v[62:63]
	v_pk_fma_f32 v[156:157], v[156:157], v[92:93], v[124:125]
	v_pk_fma_f32 v[158:159], v[158:159], v[94:95], v[126:127]
	v_cvt_pk_bf16_f32 v206, v156, v157
	v_cvt_pk_bf16_f32 v207, v158, v159
	global_store_dwordx4 v4, v[204:207], s[12:13] offset:3072
	s_cmp_eq_u32 s16, 0
	s_cbranch_scc1 .LBB0_64
	s_mov_b32 s3, s17

; DI unsigned pk2(float lo, float hi) { f32x2 v = {lo, hi}; bfv2 r = __builtin_convertvector(v, bfv2); return __builtin_bit_cast(unsigned, r); }
; DI float wave_sum(float v) { for (int m = 32; m >= 1; m >>= 1) v += __shfl_xor(v, m, 64); return v; }
; DI void phase_pre(const P& p, int bid, int nb) {
;     ...
;     f32x4 v[8]; float ss = 0.f;
; #pragma unroll
;     for (int q = 0; q < 8; ++q) { v[q] = *(const f32x4*)(src + q * 256 + lane * 4); ss += v[q].x * v[q].x + v[q].y * v[q].y + v[q].z * v[q].z + v[q].w * v[q].w; }
;     ss = wave_sum(ss); const float rstd = rsqrtf(ss * (1.f / 2048.f) + 1e-6f);
;     const float* sh = MOD + mrow * 12288; const float* sc = sh + 2048;
; #pragma unroll
;     for (int q = 0; q < 8; ++q) { int idx = q * 256 + lane * 4; f32x4 w = *(const f32x4*)(p.n_pre_mix + idx), s1 = *(const f32x4*)(sc + idx), h1 = *(const f32x4*)(sh + idx);
;       f32x4 y = v[q] * rstd * w * (1.f + s1) + h1; u32x2 o; o.x = pk2(y.x, y.y); o.y = pk2(y.z, y.w); *(u32x2*)(HX + (size_t)row * D + idx) = o; }
.Lpre_mok_B:
	s_add_i32 s17, s3, s6
	s_cmp_lt_i32 s17, s23
	s_cselect_b32 s16, 1, 0
	s_cselect_b32 s19, s17, s3
	s_cmp_lt_i32 s19, s22
	s_cselect_b32 s24, s68, s72
	s_cselect_b32 s25, s69, s73
	s_cselect_b32 s18, 0, s22
	s_sub_i32 s18, s19, s18
	s_lshl_b32 s18, s18, 13
	s_add_u32 s8, s24, s18
	s_addc_u32 s9, s25, 0
	s_add_u32 s10, s8, 0x1000
	s_addc_u32 s11, s9, 0
	s_lshl_b32 s18, s3, 12
	s_add_u32 s12, s84, s18
	s_addc_u32 s13, s85, 0
	s_add_u32 s12, s12, 0x1000000
	s_addc_u32 s13, s13, 0
	global_load_dwordx4 v[128:131], v5, s[8:9]
	global_load_dwordx4 v[132:135], v5, s[8:9] offset:16
	global_load_dwordx4 v[136:139], v5, s[8:9] offset:2048
	global_load_dwordx4 v[140:143], v5, s[8:9] offset:2064
	global_load_dwordx4 v[144:147], v5, s[10:11]
	global_load_dwordx4 v[148:151], v5, s[10:11] offset:16
	global_load_dwordx4 v[152:155], v5, s[10:11] offset:2048
	global_load_dwordx4 v[156:159], v5, s[10:11] offset:2064
	s_waitcnt vmcnt(12)
	v_mul_f32_e32 v208, v160, v160
	v_fmac_f32_e32 v208, v164, v164
	v_mul_f32_e32 v209, v168, v168
	v_fmac_f32_e32 v209, v172, v172
	v_mul_f32_e32 v210, v176, v176
	v_fmac_f32_e32 v210, v180, v180
	v_mul_f32_e32 v211, v184, v184
	v_fmac_f32_e32 v211, v188, v188
	v_fmac_f32_e32 v208, v161, v161
	v_fmac_f32_e32 v208, v165, v165
	v_fmac_f32_e32 v209, v169, v169
	v_fmac_f32_e32 v209, v173, v173
	v_fmac_f32_e32 v210, v177, v177
	v_fmac_f32_e32 v210, v181, v181
	v_fmac_f32_e32 v211, v185, v185
	v_fmac_f32_e32 v211, v189, v189
	v_fmac_f32_e32 v208, v162, v162
	v_fmac_f32_e32 v208, v166, v166
	v_fmac_f32_e32 v209, v170, v170
	v_fmac_f32_e32 v209, v174, v174
	v_fmac_f32_e32 v210, v178, v178
	v_fmac_f32_e32 v210, v182, v182
	v_fmac_f32_e32 v211, v186, v186
	v_fmac_f32_e32 v211, v190, v190
	v_fmac_f32_e32 v208, v163, v163
	v_fmac_f32_e32 v208, v167, v167
	v_fmac_f32_e32 v209, v171, v171
	v_fmac_f32_e32 v209, v175, v175
	v_fmac_f32_e32 v210, v179, v179
	v_fmac_f32_e32 v210, v183, v183
	v_fmac_f32_e32 v211, v187, v187
	v_fmac_f32_e32 v211, v191, v191
	v_add_f32_e32 v208, v208, v209
	v_add_f32_e32 v210, v210, v211
	v_add_f32_e32 v208, v208, v210
	ds_bpermute_b32 v212, v6, v208
	s_waitcnt lgkmcnt(0)
	v_add_f32_e32 v208, v208, v212
	ds_bpermute_b32 v212, v7, v208
	s_waitcnt lgkmcnt(0)
	v_add_f32_e32 v208, v208, v212
	ds_bpermute_b32 v212, v8, v208
	s_waitcnt lgkmcnt(0)
	v_add_f32_e32 v208, v208, v212
	ds_bpermute_b32 v212, v9, v208
	s_waitcnt lgkmcnt(0)
	v_add_f32_e32 v208, v208, v212
	ds_bpermute_b32 v212, v10, v208
	s_waitcnt lgkmcnt(0)
	v_add_f32_e32 v208, v208, v212
	ds_bpermute_b32 v212, v11, v208
	s_waitcnt lgkmcnt(0)
	v_add_f32_e32 v208, v208, v212
	v_mov_b32_e32 v212, 0x358637bd
	v_fmac_f32_e32 v212, 0x3a000000, v208
	v_rsq_f32_e32 v214, v212
	s_nop 0
	v_pk_mul_f32 v[160:161], v[214:215], v[160:161] op_sel_hi:[0,1]
	v_pk_mul_f32 v[162:163], v[214:215], v[162:163] op_sel_hi:[0,1]
	v_pk_mul_f32 v[160:161], v[160:161], v[32:33]
	v_pk_mul_f32 v[162:163], v[162:163], v[34:35]
	v_pk_fma_f32 v[160:161], v[160:161], v[64:65], v[96:97]
	v_pk_fma_f32 v[162:163], v[162:163], v[66:67], v[98:99]
	v_cvt_pk_bf16_f32 v192, v160, v161
	v_cvt_pk_bf16_f32 v193, v162, v163
	v_pk_mul_f32 v[164:165], v[214:215], v[164:165] op_sel_hi:[0,1]
	v_pk_mul_f32 v[166:167], v[214:215], v[166:167] op_sel_hi:[0,1]
	v_pk_mul_f32 v[164:165], v[164:165], v[36:37]
	v_pk_mul_f32 v[166:167], v[166:167], v[38:39]
	v_pk_fma_f32 v[164:165], v[164:165], v[68:69], v[100:101]
	v_pk_fma_f32 v[166:167], v[166:167], v[70:71], v[102:103]
	v_cvt_pk_bf16_f32 v194, v164, v165
	v_cvt_pk_bf16_f32 v195, v166, v167
	global_store_dwordx4 v4, v[192:195], s[12:13]
	v_pk_mul_f32 v[168:169], v[214:215], v[168:169] op_sel_hi:[0,1]
	v_pk_mul_f32 v[170:171], v[214:215], v[170:171] op_sel_hi:[0,1]
	v_pk_mul_f32 v[168:169], v[168:169], v[40:41]
	v_pk_mul_f32 v[170:171], v[170:171], v[42:43]
	v_pk_fma_f32 v[168:169], v[168:169], v[72:73], v[104:105]
	v_pk_fma_f32 v[170:171], v[170:171], v[74:75], v[106:107]
	v_cvt_pk_bf16_f32 v196, v168, v169
	v_cvt_pk_bf16_f32 v197, v170, v171
	v_pk_mul_f32 v[172:173], v[214:215], v[172:173] op_sel_hi:[0,1]
	v_pk_mul_f32 v[174:175], v[214:215], v[174:175] op_sel_hi:[0,1]
	v_pk_mul_f32 v[172:173], v[172:173], v[44:45]
	v_pk_mul_f32 v[174:175], v[174:175], v[46:47]
	v_pk_fma_f32 v[172:173], v[172:173], v[76:77], v[108:109]
	v_pk_fma_f32 v[174:175], v[174:175], v[78:79], v[110:111]
	v_cvt_pk_bf16_f32 v198, v172, v173
	v_cvt_pk_bf16_f32 v199, v174, v175
	global_store_dwordx4 v4, v[196:199], s[12:13] offset:1024
	v_pk_mul_f32 v[176:177], v[214:215], v[176:177] op_sel_hi:[0,1]
	v_pk_mul_f32 v[178:179], v[214:215], v[178:179] op_sel_hi:[0,1]
	v_pk_mul_f32 v[176:177], v[176:177], v[48:49]
	v_pk_mul_f32 v[178:179], v[178:179], v[50:51]
	v_pk_fma_f32 v[176:177], v[176:177], v[80:81], v[112:113]
	v_pk_fma_f32 v[178:179], v[178:179], v[82:83], v[114:115]
	v_cvt_pk_bf16_f32 v200, v176, v177
	v_cvt_pk_bf16_f32 v201, v178, v179
	v_pk_mul_f32 v[180:181], v[214:215], v[180:181] op_sel_hi:[0,1]
	v_pk_mul_f32 v[182:183], v[214:215], v[182:183] op_sel_hi:[0,1]
	v_pk_mul_f32 v[180:181], v[180:181], v[52:53]
	v_pk_mul_f32 v[182:183], v[182:183], v[54:55]
	v_pk_fma_f32 v[180:181], v[180:181], v[84:85], v[116:117]
	v_pk_fma_f32 v[182:183], v[182:183], v[86:87], v[118:119]
	v_cvt_pk_bf16_f32 v202, v180, v181
	v_cvt_pk_bf16_f32 v203, v182, v183
	global_store_dwordx4 v4, v[200:203], s[12:13] offset:2048
	v_pk_mul_f32 v[184:185], v[214:215], v[184:185] op_sel_hi:[0,1]
	v_pk_mul_f32 v[186:187], v[214:215], v[186:187] op_sel_hi:[0,1]
	v_pk_mul_f32 v[184:185], v[184:185], v[56:57]
	v_pk_mul_f32 v[186:187], v[186:187], v[58:59]
	v_pk_fma_f32 v[184:185], v[184:185], v[88:89], v[120:121]
	v_pk_fma_f32 v[186:187], v[186:187], v[90:91], v[122:123]
	v_cvt_pk_bf16_f32 v204, v184, v185
	v_cvt_pk_bf16_f32 v205, v186, v187
	v_pk_mul_f32 v[188:189], v[214:215], v[188:189] op_sel_hi:[0,1]
	v_pk_mul_f32 v[190:191], v[214:215], v[190:191] op_sel_hi:[0,1]
	v_pk_mul_f32 v[188:189], v[188:189], v[60:61]
	v_pk_mul_f32 v[190:191], v[190:191], v[62:63]
	v_pk_fma_f32 v[188:189], v[188:189], v[92:93], v[124:125]
	v_pk_fma_f32 v[190:191], v[190:191], v[94:95], v[126:127]
	v_cvt_pk_bf16_f32 v206, v188, v189
	v_cvt_pk_bf16_f32 v207, v190, v191
	global_store_dwordx4 v4, v[204:207], s[12:13] offset:3072
	s_cmp_eq_u32 s16, 0
	s_cbranch_scc1 .LBB0_64
	s_mov_b32 s3, s17
	s_branch .Lpre_half_A

; DI float bflo(unsigned u) { return __uint_as_float(u << 16); }
; DI float bfhi(unsigned u) { return __uint_as_float(u & 0xffff0000u); }
; DI float wave_sum(float v) { for (int m = 32; m >= 1; m >>= 1) v += __shfl_xor(v, m, 64); return v; }
; DI void phase_rowmid(const P& p, int bid, int nb) {
;     ...
;   for (int row = bid * 8 + wid; row < T; row += nb * 8) {
;     const float* md = MOD + (row >> 14) * 12288;
;     float mv[32]; float ss = 0.f;
; #pragma unroll
;     for (int q = 0; q < 4; ++q) { u32x4 a = *(const u32x4*)(MIX + (size_t)row * 2048 + q * 512 + lane * 8);
; #pragma unroll
;       for (int e = 0; e < 4; ++e) { mv[q * 8 + 2 * e] = bflo(a[e]); mv[q * 8 + 2 * e + 1] = bfhi(a[e]); } }
; #pragma unroll
;     for (int e = 0; e < 32; ++e) ss += mv[e] * mv[e];
;     ss = wave_sum(ss); const float rstd = rsqrtf(ss * (1.f / 2048.f) + 1e-6f);
;     float ss2 = 0.f;
; #pragma unroll
;     for (int q = 0; q < 4; ++q)
; #pragma unroll
;       for (int hh = 0; hh < 2; ++hh) { const int idx = q * 512 + lane * 8 + hh * 4;
;         f32x4 xv = *(const f32x4*)(p.x + (size_t)row * 2048 + idx), w = *(const f32x4*)(p.n_post_mix + idx), g1 = *(const f32x4*)(md + 4096 + idx);
; #pragma unroll
;         for (int e = 0; e < 4; ++e) { float x1 = xv[e] + g1[e] * (mv[q * 8 + hh * 4 + e] * rstd * w[e]); mv[q * 8 + hh * 4 + e] = x1; ss2 += x1 * x1; } }
.LBB0_607:
	s_waitcnt vmcnt(0)
	v_lshrrev_b32_e32 v5, 6, v4
	s_lshl_b32 s8, s2, 3
	v_add_u32_e32 v12, s8, v5
	v_and_b32_e32 v3, 63, v4
	v_lshlrev_b32_e32 v1, 4, v3
	v_readfirstlane_b32 s3, v12
	v_lshlrev_b32_e32 v2, 5, v3
	v_xor_b32_e32 v6, 32, v3
	v_lshlrev_b32_e32 v6, 2, v6
	v_xor_b32_e32 v7, 16, v3
	v_lshlrev_b32_e32 v7, 2, v7
	v_xor_b32_e32 v8, 8, v3
	v_lshlrev_b32_e32 v8, 2, v8
	v_xor_b32_e32 v9, 4, v3
	v_lshlrev_b32_e32 v9, 2, v9
	v_xor_b32_e32 v10, 2, v3
	v_lshlrev_b32_e32 v10, 2, v10
	v_xor_b32_e32 v11, 1, v3
	v_lshlrev_b32_e32 v11, 2, v11
	s_lshl_b32 s4, s88, 3
	s_mov_b32 s18, 0x8000
	s_cmp_ge_i32 s3, s18
	s_cbranch_scc1 .Lmid_done
	v_readlane_b32 s22, v254, 16
	v_readlane_b32 s23, v254, 17
	s_mov_b32 s5, -1
	s_add_u32 s20, s82, 0x1000
	s_addc_u32 s21, s83, 0
	s_add_u32 s24, s22, 0x1000
	s_addc_u32 s25, s23, 0
	s_lshl_b32 s19, s3, 12
	s_add_u32 s8, s84, s19
	s_addc_u32 s9, s85, 0
	s_add_u32 s8, s8, 0x1bd00000
	s_addc_u32 s9, s9, 0
	s_lshl_b32 s19, s3, 13
	s_add_u32 s10, s68, s19
	s_addc_u32 s11, s69, 0
	s_add_u32 s12, s10, 0x1000
	s_addc_u32 s13, s11, 0
	global_load_dwordx4 v[112:115], v1, s[8:9]
	global_load_dwordx4 v[116:119], v1, s[8:9] offset:1024
	global_load_dwordx4 v[120:123], v1, s[8:9] offset:2048
	global_load_dwordx4 v[124:127], v1, s[8:9] offset:3072
	global_load_dwordx4 v[128:131], v2, s[10:11]
	global_load_dwordx4 v[132:135], v2, s[10:11] offset:16
	global_load_dwordx4 v[136:139], v2, s[10:11] offset:2048
	global_load_dwordx4 v[140:143], v2, s[10:11] offset:2064
	global_load_dwordx4 v[144:147], v2, s[12:13]
	global_load_dwordx4 v[148:151], v2, s[12:13] offset:16
	global_load_dwordx4 v[152:155], v2, s[12:13] offset:2048
	global_load_dwordx4 v[156:159], v2, s[12:13] offset:2064
.Lmid_loop:
	s_lshr_b32 s19, s3, 14
	s_cmp_eq_u32 s19, s5
	s_cbranch_scc1 .Lmid_cok
	s_mov_b32 s5, s19
	s_mul_i32 s19, s19, 0xc000
	s_add_u32 s16, s84, s19
	s_addc_u32 s17, s85, 0
	s_add_u32 s26, s16, 0x4000
	s_addc_u32 s27, s17, 0
	global_load_dwordx4 v[16:19], v2, s[26:27]
	global_load_dwordx4 v[20:23], v2, s[26:27] offset:16
	global_load_dwordx4 v[24:27], v2, s[26:27] offset:2048
	global_load_dwordx4 v[28:31], v2, s[26:27] offset:2064
	s_add_u32 s26, s26, 0x1000
	s_addc_u32 s27, s27, 0
	global_load_dwordx4 v[32:35], v2, s[26:27]
	global_load_dwordx4 v[36:39], v2, s[26:27] offset:16
	global_load_dwordx4 v[40:43], v2, s[26:27] offset:2048
	global_load_dwordx4 v[44:47], v2, s[26:27] offset:2064
	s_add_u32 s26, s16, 0x6000
	s_addc_u32 s27, s17, 0
	global_load_dwordx4 v[80:83], v2, s[26:27]
	global_load_dwordx4 v[84:87], v2, s[26:27] offset:16
	global_load_dwordx4 v[88:91], v2, s[26:27] offset:2048
	global_load_dwordx4 v[92:95], v2, s[26:27] offset:2064
	s_add_u32 s26, s26, 0x1000
	s_addc_u32 s27, s27, 0
	global_load_dwordx4 v[96:99], v2, s[26:27]
	global_load_dwordx4 v[100:103], v2, s[26:27] offset:16
	global_load_dwordx4 v[104:107], v2, s[26:27] offset:2048
	global_load_dwordx4 v[108:111], v2, s[26:27] offset:2064
	s_add_u32 s26, s16, 0x8000
	s_addc_u32 s27, s17, 0
	global_load_dwordx4 v[48:51], v2, s[26:27]
	global_load_dwordx4 v[52:55], v2, s[26:27] offset:16
	global_load_dwordx4 v[56:59], v2, s[26:27] offset:2048
	global_load_dwordx4 v[60:63], v2, s[26:27] offset:2064
	s_add_u32 s26, s26, 0x1000
	s_addc_u32 s27, s27, 0
	global_load_dwordx4 v[64:67], v2, s[26:27]
	global_load_dwordx4 v[68:71], v2, s[26:27] offset:16
	global_load_dwordx4 v[72:75], v2, s[26:27] offset:2048
	global_load_dwordx4 v[76:79], v2, s[26:27] offset:2064
	global_load_dwordx4 v[160:163], v2, s[82:83]
	global_load_dwordx4 v[164:167], v2, s[82:83] offset:16
	global_load_dwordx4 v[168:171], v2, s[82:83] offset:2048
	global_load_dwordx4 v[172:175], v2, s[82:83] offset:2064
	global_load_dwordx4 v[176:179], v2, s[20:21]
	global_load_dwordx4 v[180:183], v2, s[20:21] offset:16
	global_load_dwordx4 v[184:187], v2, s[20:21] offset:2048
	global_load_dwordx4 v[188:191], v2, s[20:21] offset:2064
	global_load_dwordx4 v[192:195], v2, s[22:23]
	global_load_dwordx4 v[196:199], v2, s[22:23] offset:16
	global_load_dwordx4 v[200:203], v2, s[22:23] offset:2048
	global_load_dwordx4 v[204:207], v2, s[22:23] offset:2064
	global_load_dwordx4 v[208:211], v2, s[24:25]
	global_load_dwordx4 v[212:215], v2, s[24:25] offset:16
	global_load_dwordx4 v[216:219], v2, s[24:25] offset:2048
	global_load_dwordx4 v[220:223], v2, s[24:25] offset:2064
	s_waitcnt vmcnt(0)
	v_pk_mul_f32 v[16:17], v[16:17], v[160:161]
	v_pk_add_f32 v[48:49], v[48:49], 1.0 op_sel_hi:[1,0]
	v_pk_mul_f32 v[48:49], v[192:193], v[48:49]
	v_pk_mul_f32 v[18:19], v[18:19], v[162:163]
	v_pk_add_f32 v[50:51], v[50:51], 1.0 op_sel_hi:[1,0]
	v_pk_mul_f32 v[50:51], v[194:195], v[50:51]
	v_pk_mul_f32 v[20:21], v[20:21], v[164:165]
	v_pk_add_f32 v[52:53], v[52:53], 1.0 op_sel_hi:[1,0]
	v_pk_mul_f32 v[52:53], v[196:197], v[52:53]
	v_pk_mul_f32 v[22:23], v[22:23], v[166:167]
	v_pk_add_f32 v[54:55], v[54:55], 1.0 op_sel_hi:[1,0]
	v_pk_mul_f32 v[54:55], v[198:199], v[54:55]
	v_pk_mul_f32 v[24:25], v[24:25], v[168:169]
	v_pk_add_f32 v[56:57], v[56:57], 1.0 op_sel_hi:[1,0]
	v_pk_mul_f32 v[56:57], v[200:201], v[56:57]
	v_pk_mul_f32 v[26:27], v[26:27], v[170:171]
	v_pk_add_f32 v[58:59], v[58:59], 1.0 op_sel_hi:[1,0]
	v_pk_mul_f32 v[58:59], v[202:203], v[58:59]
	v_pk_mul_f32 v[28:29], v[28:29], v[172:173]
	v_pk_add_f32 v[60:61], v[60:61], 1.0 op_sel_hi:[1,0]
	v_pk_mul_f32 v[60:61], v[204:205], v[60:61]
	v_pk_mul_f32 v[30:31], v[30:31], v[174:175]
	v_pk_add_f32 v[62:63], v[62:63], 1.0 op_sel_hi:[1,0]
	v_pk_mul_f32 v[62:63], v[206:207], v[62:63]
	v_pk_mul_f32 v[32:33], v[32:33], v[176:177]
	v_pk_add_f32 v[64:65], v[64:65], 1.0 op_sel_hi:[1,0]
	v_pk_mul_f32 v[64:65], v[208:209], v[64:65]
	v_pk_mul_f32 v[34:35], v[34:35], v[178:179]
	v_pk_add_f32 v[66:67], v[66:67], 1.0 op_sel_hi:[1,0]
	v_pk_mul_f32 v[66:67], v[210:211], v[66:67]
	v_pk_mul_f32 v[36:37], v[36:37], v[180:181]
	v_pk_add_f32 v[68:69], v[68:69], 1.0 op_sel_hi:[1,0]
	v_pk_mul_f32 v[68:69], v[212:213], v[68:69]
	v_pk_mul_f32 v[38:39], v[38:39], v[182:183]
	v_pk_add_f32 v[70:71], v[70:71], 1.0 op_sel_hi:[1,0]
	v_pk_mul_f32 v[70:71], v[214:215], v[70:71]
	v_pk_mul_f32 v[40:41], v[40:41], v[184:185]
	v_pk_add_f32 v[72:73], v[72:73], 1.0 op_sel_hi:[1,0]
	v_pk_mul_f32 v[72:73], v[216:217], v[72:73]
	v_pk_mul_f32 v[42:43], v[42:43], v[186:187]
	v_pk_add_f32 v[74:75], v[74:75], 1.0 op_sel_hi:[1,0]
	v_pk_mul_f32 v[74:75], v[218:219], v[74:75]
	v_pk_mul_f32 v[44:45], v[44:45], v[188:189]
	v_pk_add_f32 v[76:77], v[76:77], 1.0 op_sel_hi:[1,0]
	v_pk_mul_f32 v[76:77], v[220:221], v[76:77]
	v_pk_mul_f32 v[46:47], v[46:47], v[190:191]
	v_pk_add_f32 v[78:79], v[78:79], 1.0 op_sel_hi:[1,0]
	v_pk_mul_f32 v[78:79], v[222:223], v[78:79]
; DI float bflo(unsigned u) { return __uint_as_float(u << 16); }
; DI float bfhi(unsigned u) { return __uint_as_float(u & 0xffff0000u); }
; DI float wave_sum(float v) { for (int m = 32; m >= 1; m >>= 1) v += __shfl_xor(v, m, 64); return v; }
; DI void phase_rowmid(const P& p, int bid, int nb) {
;     ...
;     const float* md = MOD + (row >> 14) * 12288;
;     float mv[32]; float ss = 0.f;
; #pragma unroll
;     for (int q = 0; q < 4; ++q) { u32x4 a = *(const u32x4*)(MIX + (size_t)row * 2048 + q * 512 + lane * 8);
; #pragma unroll
;       for (int e = 0; e < 4; ++e) { mv[q * 8 + 2 * e] = bflo(a[e]); mv[q * 8 + 2 * e + 1] = bfhi(a[e]); } }
; #pragma unroll
;     for (int e = 0; e < 32; ++e) ss += mv[e] * mv[e];
;     ss = wave_sum(ss); const float rstd = rsqrtf(ss * (1.f / 2048.f) + 1e-6f);
;     float ss2 = 0.f;
; #pragma unroll
;     for (int q = 0; q < 4; ++q)
; #pragma unroll
;       for (int hh = 0; hh < 2; ++hh) { const int idx = q * 512 + lane * 8 + hh * 4;
;         f32x4 xv = *(const f32x4*)(p.x + (size_t)row * 2048 + idx), w = *(const f32x4*)(p.n_post_mix + idx), g1 = *(const f32x4*)(md + 4096 + idx);
; #pragma unroll
;         for (int e = 0; e < 4; ++e) { float x1 = xv[e] + g1[e] * (mv[q * 8 + hh * 4 + e] * rstd * w[e]); mv[q * 8 + hh * 4 + e] = x1; ss2 += x1 * x1; } }
.Lmid_cok:
	s_lshl_b32 s19, s3, 12
	s_add_u32 s14, s84, s19
	s_addc_u32 s15, s85, 0
	s_add_u32 s14, s14, 0xbb00000
	s_addc_u32 s15, s15, 0
	s_add_i32 s27, s3, s4
	s_cmp_lt_i32 s27, s18
	s_cselect_b32 s26, 1, 0
	s_cselect_b32 s0, s27, s3
	s_waitcnt vmcnt(12)
	v_lshlrev_b32_e32 v160, 16, v112
	v_and_b32_e32 v161, 0xffff0000, v112
	v_lshlrev_b32_e32 v162, 16, v113
	v_and_b32_e32 v163, 0xffff0000, v113
	v_lshlrev_b32_e32 v164, 16, v114
	v_and_b32_e32 v165, 0xffff0000, v114
	v_lshlrev_b32_e32 v166, 16, v115
	v_and_b32_e32 v167, 0xffff0000, v115
	v_lshlrev_b32_e32 v168, 16, v116
	v_and_b32_e32 v169, 0xffff0000, v116
	v_lshlrev_b32_e32 v170, 16, v117
	v_and_b32_e32 v171, 0xffff0000, v117
	v_lshlrev_b32_e32 v172, 16, v118
	v_and_b32_e32 v173, 0xffff0000, v118
	v_lshlrev_b32_e32 v174, 16, v119
	v_and_b32_e32 v175, 0xffff0000, v119
	v_lshlrev_b32_e32 v176, 16, v120
	v_and_b32_e32 v177, 0xffff0000, v120
	v_lshlrev_b32_e32 v178, 16, v121
	v_and_b32_e32 v179, 0xffff0000, v121
	v_lshlrev_b32_e32 v180, 16, v122
	v_and_b32_e32 v181, 0xffff0000, v122
	v_lshlrev_b32_e32 v182, 16, v123
	v_and_b32_e32 v183, 0xffff0000, v123
	v_lshlrev_b32_e32 v184, 16, v124
	v_and_b32_e32 v185, 0xffff0000, v124
	v_lshlrev_b32_e32 v186, 16, v125
	v_and_b32_e32 v187, 0xffff0000, v125
	v_lshlrev_b32_e32 v188, 16, v126
	v_and_b32_e32 v189, 0xffff0000, v126
	v_lshlrev_b32_e32 v190, 16, v127
	v_and_b32_e32 v191, 0xffff0000, v127
	v_mul_f32_e32 v224, v160, v160
	v_mul_f32_e32 v225, v168, v168
	v_mul_f32_e32 v226, v176, v176
	v_mul_f32_e32 v227, v184, v184
	v_fmac_f32_e32 v224, v161, v161
	v_fmac_f32_e32 v225, v169, v169
	v_fmac_f32_e32 v226, v177, v177
	v_fmac_f32_e32 v227, v185, v185
	v_fmac_f32_e32 v224, v162, v162
	v_fmac_f32_e32 v225, v170, v170
	v_fmac_f32_e32 v226, v178, v178
	v_fmac_f32_e32 v227, v186, v186
	v_fmac_f32_e32 v224, v163, v163
	v_fmac_f32_e32 v225, v171, v171
	v_fmac_f32_e32 v226, v179, v179
	v_fmac_f32_e32 v227, v187, v187
	v_fmac_f32_e32 v224, v164, v164
	v_fmac_f32_e32 v225, v172, v172
	v_fmac_f32_e32 v226, v180, v180
	v_fmac_f32_e32 v227, v188, v188
	v_fmac_f32_e32 v224, v165, v165
	v_fmac_f32_e32 v225, v173, v173
	v_fmac_f32_e32 v226, v181, v181
	v_fmac_f32_e32 v227, v189, v189
	v_fmac_f32_e32 v224, v166, v166
	v_fmac_f32_e32 v225, v174, v174
	v_fmac_f32_e32 v226, v182, v182
	v_fmac_f32_e32 v227, v190, v190
	v_fmac_f32_e32 v224, v167, v167
	v_fmac_f32_e32 v225, v175, v175
	v_fmac_f32_e32 v226, v183, v183
	v_fmac_f32_e32 v227, v191, v191
	v_add_f32_e32 v224, v224, v225
	v_add_f32_e32 v226, v226, v227
	v_add_f32_e32 v224, v224, v226
	ds_bpermute_b32 v228, v6, v224
	s_waitcnt lgkmcnt(0)
	v_add_f32_e32 v224, v224, v228
	ds_bpermute_b32 v228, v7, v224
	s_waitcnt lgkmcnt(0)
	v_add_f32_e32 v224, v224, v228
	ds_bpermute_b32 v228, v8, v224
	s_waitcnt lgkmcnt(0)
	v_add_f32_e32 v224, v224, v228
	ds_bpermute_b32 v228, v9, v224
	s_waitcnt lgkmcnt(0)
	v_add_f32_e32 v224, v224, v228
	ds_bpermute_b32 v228, v10, v224
	s_waitcnt lgkmcnt(0)
	v_add_f32_e32 v224, v224, v228
	ds_bpermute_b32 v228, v11, v224
	s_waitcnt lgkmcnt(0)
	v_add_f32_e32 v224, v224, v228
	v_mov_b32_e32 v228, 0x358637bd
	v_fmac_f32_e32 v228, 0x3a000000, v224
	v_rsq_f32_e32 v230, v228
	s_nop 0
	s_waitcnt vmcnt(4)
	v_pk_mul_f32 v[160:161], v[230:231], v[160:161] op_sel_hi:[0,1]
	v_pk_mul_f32 v[162:163], v[230:231], v[162:163] op_sel_hi:[0,1]
	v_pk_fma_f32 v[160:161], v[16:17], v[160:161], v[128:129]
	v_pk_fma_f32 v[162:163], v[18:19], v[162:163], v[130:131]
	v_pk_mul_f32 v[164:165], v[230:231], v[164:165] op_sel_hi:[0,1]
	v_pk_mul_f32 v[166:167], v[230:231], v[166:167] op_sel_hi:[0,1]
	v_pk_fma_f32 v[164:165], v[20:21], v[164:165], v[132:133]
	v_pk_fma_f32 v[166:167], v[22:23], v[166:167], v[134:135]
	v_pk_mul_f32 v[168:169], v[230:231], v[168:169] op_sel_hi:[0,1]
	v_pk_mul_f32 v[170:171], v[230:231], v[170:171] op_sel_hi:[0,1]
	v_pk_fma_f32 v[168:169], v[24:25], v[168:169], v[136:137]
	v_pk_fma_f32 v[170:171], v[26:27], v[170:171], v[138:139]
	v_pk_mul_f32 v[172:173], v[230:231], v[172:173] op_sel_hi:[0,1]
	v_pk_mul_f32 v[174:175], v[230:231], v[174:175] op_sel_hi:[0,1]
	v_pk_fma_f32 v[172:173], v[28:29], v[172:173], v[140:141]
	v_pk_fma_f32 v[174:175], v[30:31], v[174:175], v[142:143]
	v_pk_mul_f32 v[176:177], v[230:231], v[176:177] op_sel_hi:[0,1]
	v_pk_mul_f32 v[178:179], v[230:231], v[178:179] op_sel_hi:[0,1]
	v_pk_fma_f32 v[176:177], v[32:33], v[176:177], v[144:145]
	v_pk_fma_f32 v[178:179], v[34:35], v[178:179], v[146:147]
	v_pk_mul_f32 v[180:181], v[230:231], v[180:181] op_sel_hi:[0,1]
	v_pk_mul_f32 v[182:183], v[230:231], v[182:183] op_sel_hi:[0,1]
	v_pk_fma_f32 v[180:181], v[36:37], v[180:181], v[148:149]
	v_pk_fma_f32 v[182:183], v[38:39], v[182:183], v[150:151]
	v_pk_mul_f32 v[184:185], v[230:231], v[184:185] op_sel_hi:[0,1]
	v_pk_mul_f32 v[186:187], v[230:231], v[186:187] op_sel_hi:[0,1]
	v_pk_fma_f32 v[184:185], v[40:41], v[184:185], v[152:153]
	v_pk_fma_f32 v[186:187], v[42:43], v[186:187], v[154:155]
	v_pk_mul_f32 v[188:189], v[230:231], v[188:189] op_sel_hi:[0,1]
	v_pk_mul_f32 v[190:191], v[230:231], v[190:191] op_sel_hi:[0,1]
	v_pk_fma_f32 v[188:189], v[44:45], v[188:189], v[156:157]
	v_pk_fma_f32 v[190:191], v[46:47], v[190:191], v[158:159]
	v_cvt_pk_bf16_f32 v208, v160, v161
	v_cvt_pk_bf16_f32 v209, v162, v163
	v_cvt_pk_bf16_f32 v210, v164, v165
	v_cvt_pk_bf16_f32 v211, v166, v167
	global_store_dwordx4 v1, v[208:211], s[8:9]
	v_cvt_pk_bf16_f32 v212, v168, v169
	v_cvt_pk_bf16_f32 v213, v170, v171
	v_cvt_pk_bf16_f32 v214, v172, v173
	v_cvt_pk_bf16_f32 v215, v174, v175
	global_store_dwordx4 v1, v[212:215], s[8:9] offset:1024
	v_cvt_pk_bf16_f32 v216, v176, v177
	v_cvt_pk_bf16_f32 v217, v178, v179
; DI unsigned pk2(float lo, float hi) { f32x2 v = {lo, hi}; bfv2 r = __builtin_convertvector(v, bfv2); return __builtin_bit_cast(unsigned, r); }
; DI float wave_sum(float v) { for (int m = 32; m >= 1; m >>= 1) v += __shfl_xor(v, m, 64); return v; }
; DI void phase_rowmid(const P& p, int bid, int nb) {
;     ...
;     ss2 = wave_sum(ss2); const float rstd2 = rsqrtf(ss2 * (1.f / 2048.f) + 1e-6f);
; #pragma unroll
;     for (int q = 0; q < 4; ++q) { const int idx = q * 512 + lane * 8; float y[8];
; #pragma unroll
;       for (int hh = 0; hh < 2; ++hh) { f32x4 w = *(const f32x4*)(p.n_pre_ffn + idx + hh * 4), s2 = *(const f32x4*)(md + 8192 + idx + hh * 4), h2 = *(const f32x4*)(md + 6144 + idx + hh * 4);
; #pragma unroll
;         for (int e = 0; e < 4; ++e) y[hh * 4 + e] = mv[q * 8 + hh * 4 + e] * rstd2 * w[e] * (1.f + s2[e]) + h2[e]; }
;       u32x4 o; o.x = pk2(y[0], y[1]); o.y = pk2(y[2], y[3]); o.z = pk2(y[4], y[5]); o.w = pk2(y[6], y[7]);
;       *(u32x4*)(HX2 + (size_t)row * 2048 + idx) = o;
;       u32x4 xo; xo.x = pk2(mv[q * 8], mv[q * 8 + 1]); xo.y = pk2(mv[q * 8 + 2], mv[q * 8 + 3]); xo.z = pk2(mv[q * 8 + 4], mv[q * 8 + 5]); xo.w = pk2(mv[q * 8 + 6], mv[q * 8 + 7]);
;       *(u32x4*)(X1B + (size_t)row * 2048 + idx) = xo; }
	v_cvt_pk_bf16_f32 v218, v180, v181
	v_cvt_pk_bf16_f32 v219, v182, v183
	global_store_dwordx4 v1, v[216:219], s[8:9] offset:2048
	v_cvt_pk_bf16_f32 v220, v184, v185
	v_cvt_pk_bf16_f32 v221, v186, v187
	v_cvt_pk_bf16_f32 v222, v188, v189
	v_cvt_pk_bf16_f32 v223, v190, v191
	global_store_dwordx4 v1, v[220:223], s[8:9] offset:3072
	s_lshl_b32 s19, s0, 12
	s_add_u32 s8, s84, s19
	s_addc_u32 s9, s85, 0
	s_add_u32 s8, s8, 0x1bd00000
	s_addc_u32 s9, s9, 0
	s_lshl_b32 s19, s0, 13
	s_add_u32 s10, s68, s19
	s_addc_u32 s11, s69, 0
	s_add_u32 s12, s10, 0x1000
	s_addc_u32 s13, s11, 0
	global_load_dwordx4 v[112:115], v1, s[8:9]
	global_load_dwordx4 v[116:119], v1, s[8:9] offset:1024
	global_load_dwordx4 v[120:123], v1, s[8:9] offset:2048
	global_load_dwordx4 v[124:127], v1, s[8:9] offset:3072
	global_load_dwordx4 v[128:131], v2, s[10:11]
	global_load_dwordx4 v[132:135], v2, s[10:11] offset:16
	global_load_dwordx4 v[136:139], v2, s[10:11] offset:2048
	global_load_dwordx4 v[140:143], v2, s[10:11] offset:2064
	global_load_dwordx4 v[144:147], v2, s[12:13]
	global_load_dwordx4 v[148:151], v2, s[12:13] offset:16
	global_load_dwordx4 v[152:155], v2, s[12:13] offset:2048
	global_load_dwordx4 v[156:159], v2, s[12:13] offset:2064
	v_mul_f32_e32 v224, v160, v160
	v_mul_f32_e32 v225, v168, v168
	v_mul_f32_e32 v226, v176, v176
	v_mul_f32_e32 v227, v184, v184
	v_fmac_f32_e32 v224, v161, v161
	v_fmac_f32_e32 v225, v169, v169
	v_fmac_f32_e32 v226, v177, v177
	v_fmac_f32_e32 v227, v185, v185
	v_fmac_f32_e32 v224, v162, v162
	v_fmac_f32_e32 v225, v170, v170
	v_fmac_f32_e32 v226, v178, v178
	v_fmac_f32_e32 v227, v186, v186
	v_fmac_f32_e32 v224, v163, v163
	v_fmac_f32_e32 v225, v171, v171
	v_fmac_f32_e32 v226, v179, v179
	v_fmac_f32_e32 v227, v187, v187
	v_fmac_f32_e32 v224, v164, v164
	v_fmac_f32_e32 v225, v172, v172
	v_fmac_f32_e32 v226, v180, v180
	v_fmac_f32_e32 v227, v188, v188
	v_fmac_f32_e32 v224, v165, v165
	v_fmac_f32_e32 v225, v173, v173
	v_fmac_f32_e32 v226, v181, v181
	v_fmac_f32_e32 v227, v189, v189
	v_fmac_f32_e32 v224, v166, v166
	v_fmac_f32_e32 v225, v174, v174
	v_fmac_f32_e32 v226, v182, v182
	v_fmac_f32_e32 v227, v190, v190
	v_fmac_f32_e32 v224, v167, v167
	v_fmac_f32_e32 v225, v175, v175
	v_fmac_f32_e32 v226, v183, v183
	v_fmac_f32_e32 v227, v191, v191
	v_add_f32_e32 v224, v224, v225
	v_add_f32_e32 v226, v226, v227
	v_add_f32_e32 v224, v224, v226
	ds_bpermute_b32 v228, v6, v224
	s_waitcnt lgkmcnt(0)
	v_add_f32_e32 v224, v224, v228
	ds_bpermute_b32 v228, v7, v224
	s_waitcnt lgkmcnt(0)
	v_add_f32_e32 v224, v224, v228
	ds_bpermute_b32 v228, v8, v224
	s_waitcnt lgkmcnt(0)
	v_add_f32_e32 v224, v224, v228
	ds_bpermute_b32 v228, v9, v224
	s_waitcnt lgkmcnt(0)
	v_add_f32_e32 v224, v224, v228
	ds_bpermute_b32 v228, v10, v224
	s_waitcnt lgkmcnt(0)
	v_add_f32_e32 v224, v224, v228
	ds_bpermute_b32 v228, v11, v224
	s_waitcnt lgkmcnt(0)
	v_add_f32_e32 v224, v224, v228
	v_mov_b32_e32 v228, 0x358637bd
	v_fmac_f32_e32 v228, 0x3a000000, v224
	v_rsq_f32_e32 v232, v228
	s_nop 0
	v_pk_mul_f32 v[160:161], v[232:233], v[160:161] op_sel_hi:[0,1]
	v_pk_mul_f32 v[162:163], v[232:233], v[162:163] op_sel_hi:[0,1]
	v_pk_fma_f32 v[160:161], v[160:161], v[48:49], v[80:81]
	v_pk_fma_f32 v[162:163], v[162:163], v[50:51], v[82:83]
	v_pk_mul_f32 v[164:165], v[232:233], v[164:165] op_sel_hi:[0,1]
	v_pk_mul_f32 v[166:167], v[232:233], v[166:167] op_sel_hi:[0,1]
	v_pk_fma_f32 v[164:165], v[164:165], v[52:53], v[84:85]
	v_pk_fma_f32 v[166:167], v[166:167], v[54:55], v[86:87]
	v_pk_mul_f32 v[168:169], v[232:233], v[168:169] op_sel_hi:[0,1]
	v_pk_mul_f32 v[170:171], v[232:233], v[170:171] op_sel_hi:[0,1]
	v_pk_fma_f32 v[168:169], v[168:169], v[56:57], v[88:89]
	v_pk_fma_f32 v[170:171], v[170:171], v[58:59], v[90:91]
	v_pk_mul_f32 v[172:173], v[232:233], v[172:173] op_sel_hi:[0,1]
	v_pk_mul_f32 v[174:175], v[232:233], v[174:175] op_sel_hi:[0,1]
	v_pk_fma_f32 v[172:173], v[172:173], v[60:61], v[92:93]
	v_pk_fma_f32 v[174:175], v[174:175], v[62:63], v[94:95]
	v_pk_mul_f32 v[176:177], v[232:233], v[176:177] op_sel_hi:[0,1]
	v_pk_mul_f32 v[178:179], v[232:233], v[178:179] op_sel_hi:[0,1]
	v_pk_fma_f32 v[176:177], v[176:177], v[64:65], v[96:97]
	v_pk_fma_f32 v[178:179], v[178:179], v[66:67], v[98:99]
	v_pk_mul_f32 v[180:181], v[232:233], v[180:181] op_sel_hi:[0,1]
	v_pk_mul_f32 v[182:183], v[232:233], v[182:183] op_sel_hi:[0,1]
	v_pk_fma_f32 v[180:181], v[180:181], v[68:69], v[100:101]
	v_pk_fma_f32 v[182:183], v[182:183], v[70:71], v[102:103]
	v_pk_mul_f32 v[184:185], v[232:233], v[184:185] op_sel_hi:[0,1]
	v_pk_mul_f32 v[186:187], v[232:233], v[186:187] op_sel_hi:[0,1]
	v_pk_fma_f32 v[184:185], v[184:185], v[72:73], v[104:105]
	v_pk_fma_f32 v[186:187], v[186:187], v[74:75], v[106:107]
	v_pk_mul_f32 v[188:189], v[232:233], v[188:189] op_sel_hi:[0,1]
	v_pk_mul_f32 v[190:191], v[232:233], v[190:191] op_sel_hi:[0,1]
	v_pk_fma_f32 v[188:189], v[188:189], v[76:77], v[108:109]
	v_pk_fma_f32 v[190:191], v[190:191], v[78:79], v[110:111]
	v_cvt_pk_bf16_f32 v192, v160, v161
	v_cvt_pk_bf16_f32 v193, v162, v163
	v_cvt_pk_bf16_f32 v194, v164, v165
	v_cvt_pk_bf16_f32 v195, v166, v167
	global_store_dwordx4 v1, v[192:195], s[14:15]
	v_cvt_pk_bf16_f32 v196, v168, v169
	v_cvt_pk_bf16_f32 v197, v170, v171
	v_cvt_pk_bf16_f32 v198, v172, v173
	v_cvt_pk_bf16_f32 v199, v174, v175
	global_store_dwordx4 v1, v[196:199], s[14:15] offset:1024
	v_cvt_pk_bf16_f32 v200, v176, v177
	v_cvt_pk_bf16_f32 v201, v178, v179
	v_cvt_pk_bf16_f32 v202, v180, v181
	v_cvt_pk_bf16_f32 v203, v182, v183
	global_store_dwordx4 v1, v[200:203], s[14:15] offset:2048
	v_cvt_pk_bf16_f32 v204, v184, v185
	v_cvt_pk_bf16_f32 v205, v186, v187
	v_cvt_pk_bf16_f32 v206, v188, v189
	v_cvt_pk_bf16_f32 v207, v190, v191
	global_store_dwordx4 v1, v[204:207], s[14:15] offset:3072
	s_cmp_eq_u32 s26, 0
	s_cbranch_scc1 .Lmid_done
	s_mov_b32 s3, s27
	s_branch .Lmid_loop
.Lmid_done:
	s_mov_b64 s[0:1], exec
